# attention loop: every exp result added straight into the per-half-wave running row sum (no per-tile combine / cross-half exchange), 16-op max tree; threshold 8 as before
# speedup vs baseline: 1.0163x; 1.0070x over previous
.Latt_loop:
	s_waitcnt vmcnt(0)
	s_barrier
	ds_read_b128 v[64:67], v173 offset:24576
	ds_read_b128 v[68:71], v173 offset:28672
	s_mov_b32 m0, s44
	ds_read_b128 v[72:75], v171 offset:24576
	global_load_lds_dwordx4 v200, s[40:41]
	s_add_u32 m0, s44, 0x400
	ds_read_b128 v[76:79], v171 offset:28672
	global_load_lds_dwordx4 v190, s[40:41]
	s_mov_b32 m0, s45
	ds_read_b128 v[216:219], v169 offset:24576
	global_load_lds_dwordx4 v192, s[42:43]
	s_add_u32 m0, s45, 0x400
	ds_read_b128 v[220:223], v169 offset:28672
	global_load_lds_dwordx4 v194, s[42:43]
	s_add_u32 m0, s45, 0x800
	ds_read_b128 v[224:227], v167 offset:24576
	global_load_lds_dwordx4 v196, s[42:43]
	s_add_u32 m0, s45, 0xc00
	ds_read_b128 v[228:231], v167 offset:28672
	global_load_lds_dwordx4 v198, s[42:43]
	ds_read_b128 v[232:235], v173 offset:32768
	ds_read_b128 v[236:239], v173 offset:36864
	ds_read_b128 v[240:243], v173 offset:40960
	ds_read_b128 v[244:247], v173 offset:45056
	s_add_u32 s40, s40, 0x18000
	s_addc_u32 s41, s41, 0
	s_add_u32 s42, s42, 0x80
	s_addc_u32 s43, s43, 0
	s_waitcnt lgkmcnt(11)
	v_mfma_f32_32x32x16_bf16 v[112:127], v[64:67], v[140:143], v[96:111]
	ds_read_b128 v[64:67], v171 offset:32768
	s_waitcnt lgkmcnt(11)
	v_mfma_f32_32x32x16_bf16 v[80:95], v[68:71], v[140:143], v[96:111]
	ds_read_b128 v[68:71], v171 offset:36864
	s_waitcnt lgkmcnt(11)
	v_mfma_f32_32x32x16_bf16 v[112:127], v[72:75], v[136:139], v[112:127]
	ds_read_b128 v[72:75], v171 offset:40960
	s_waitcnt lgkmcnt(11)
	v_mfma_f32_32x32x16_bf16 v[80:95], v[76:79], v[136:139], v[80:95]
	ds_read_b128 v[76:79], v171 offset:45056
	s_waitcnt lgkmcnt(11)
	v_mfma_f32_32x32x16_bf16 v[112:127], v[216:219], v[132:135], v[112:127]
	ds_read_b128 v[216:219], v169 offset:32768
	s_waitcnt lgkmcnt(11)
	v_mfma_f32_32x32x16_bf16 v[80:95], v[220:223], v[132:135], v[80:95]
	ds_read_b128 v[220:223], v169 offset:36864
	s_waitcnt lgkmcnt(11)
	v_mfma_f32_32x32x16_bf16 v[112:127], v[224:227], v[128:131], v[112:127]
	ds_read_b128 v[224:227], v169 offset:40960
	s_waitcnt lgkmcnt(11)
	v_mfma_f32_32x32x16_bf16 v[80:95], v[228:231], v[128:131], v[80:95]
	ds_read_b128 v[228:231], v169 offset:45056
	s_nop 7
	s_nop 3
	v_max3_f32 v175, v112, v113, v114
	v_max3_f32 v177, v115, v116, v117
	v_max3_f32 v179, v118, v119, v120
	v_max3_f32 v181, v121, v122, v123
	v_max3_f32 v248, v124, v125, v126
	v_max3_f32 v249, v127, v80, v81
	v_max3_f32 v250, v82, v83, v84
	v_max3_f32 v251, v85, v86, v87
	v_max3_f32 v253, v88, v89, v90
	v_max3_f32 v254, v91, v92, v93
	v_max3_f32 v175, v175, v177, v179
	v_max3_f32 v181, v181, v248, v249
	v_max3_f32 v250, v250, v251, v253
	v_max3_f32 v254, v254, v94, v95
	v_max3_f32 v175, v175, v181, v250
	v_max_f32_e32 v175, v175, v254
	v_cmp_lt_f32_e32 vcc, 0x41000000, v175
	s_cbranch_vccnz .Latt_resc_a
.Latt_cont_a:
	v_exp_f32_e32 v112, v112
	v_exp_f32_e32 v113, v113
	v_exp_f32_e32 v114, v114
	v_exp_f32_e32 v115, v115
	v_exp_f32_e32 v116, v116
	v_exp_f32_e32 v117, v117
	v_exp_f32_e32 v118, v118
	v_exp_f32_e32 v119, v119
	v_add_f32_e32 v189, v189, v112
	v_add_f32_e32 v189, v189, v113
	v_add_f32_e32 v189, v189, v114
	v_add_f32_e32 v189, v189, v115
	v_add_f32_e32 v189, v189, v116
	v_add_f32_e32 v189, v189, v117
	v_add_f32_e32 v189, v189, v118
	v_add_f32_e32 v189, v189, v119
	v_cvt_pk_bf16_f32 v112, v112, v113
	v_cvt_pk_bf16_f32 v113, v114, v115
	v_cvt_pk_bf16_f32 v114, v116, v117
	v_cvt_pk_bf16_f32 v115, v118, v119
	v_exp_f32_e32 v120, v120
	v_exp_f32_e32 v121, v121
	s_waitcnt lgkmcnt(8)
	v_mfma_f32_32x32x16_bf16 v[48:63], v[232:235], v[112:115], v[48:63]
	v_exp_f32_e32 v122, v122
	v_exp_f32_e32 v123, v123
	v_exp_f32_e32 v124, v124
	v_mfma_f32_32x32x16_bf16 v[32:47], v[236:239], v[112:115], v[32:47]
	v_exp_f32_e32 v125, v125
	v_exp_f32_e32 v126, v126
	v_exp_f32_e32 v127, v127
	v_mfma_f32_32x32x16_bf16 v[16:31], v[240:243], v[112:115], v[16:31]
	v_add_f32_e32 v189, v189, v120
	v_add_f32_e32 v189, v189, v121
	v_add_f32_e32 v189, v189, v122
	v_add_f32_e32 v189, v189, v123
	v_add_f32_e32 v189, v189, v124
	v_add_f32_e32 v189, v189, v125
	v_mfma_f32_32x32x16_bf16 v[0:15], v[244:247], v[112:115], v[0:15]
	ds_read_b128 v[232:235], v167 offset:32768
	ds_read_b128 v[236:239], v167 offset:36864
	ds_read_b128 v[240:243], v167 offset:40960
	ds_read_b128 v[244:247], v167 offset:45056
	v_add_f32_e32 v189, v189, v126
	v_add_f32_e32 v189, v189, v127
	v_cvt_pk_bf16_f32 v116, v120, v121
	v_cvt_pk_bf16_f32 v117, v122, v123
	v_cvt_pk_bf16_f32 v118, v124, v125
	v_cvt_pk_bf16_f32 v119, v126, v127
	s_nop 0
	s_waitcnt lgkmcnt(8)
	v_mfma_f32_32x32x16_bf16 v[48:63], v[64:67], v[116:119], v[48:63]
	v_exp_f32_e32 v80, v80
	v_exp_f32_e32 v81, v81
	v_exp_f32_e32 v82, v82
	v_mfma_f32_32x32x16_bf16 v[32:47], v[68:71], v[116:119], v[32:47]
	v_exp_f32_e32 v83, v83
	v_exp_f32_e32 v84, v84
	v_exp_f32_e32 v85, v85
	v_mfma_f32_32x32x16_bf16 v[16:31], v[72:75], v[116:119], v[16:31]
	v_exp_f32_e32 v86, v86
	v_exp_f32_e32 v87, v87
	v_add_f32_e32 v189, v189, v80
	v_add_f32_e32 v189, v189, v81
	v_mfma_f32_32x32x16_bf16 v[0:15], v[76:79], v[116:119], v[0:15]
	v_add_f32_e32 v189, v189, v82
	v_add_f32_e32 v189, v189, v83
	v_add_f32_e32 v189, v189, v84
	v_add_f32_e32 v189, v189, v85
	v_add_f32_e32 v189, v189, v86
	v_add_f32_e32 v189, v189, v87
	v_cvt_pk_bf16_f32 v80, v80, v81
	v_cvt_pk_bf16_f32 v81, v82, v83
	v_cvt_pk_bf16_f32 v82, v84, v85
	v_cvt_pk_bf16_f32 v83, v86, v87
	s_nop 0
	s_waitcnt lgkmcnt(4)
	v_mfma_f32_32x32x16_bf16 v[48:63], v[216:219], v[80:83], v[48:63]
	v_exp_f32_e32 v88, v88
	v_exp_f32_e32 v89, v89
	v_exp_f32_e32 v90, v90
	v_mfma_f32_32x32x16_bf16 v[32:47], v[220:223], v[80:83], v[32:47]
	v_exp_f32_e32 v91, v91
	v_exp_f32_e32 v92, v92
	v_exp_f32_e32 v93, v93
	v_mfma_f32_32x32x16_bf16 v[16:31], v[224:227], v[80:83], v[16:31]
	v_exp_f32_e32 v94, v94
	v_exp_f32_e32 v95, v95
	v_add_f32_e32 v189, v189, v88
	v_add_f32_e32 v189, v189, v89
	v_mfma_f32_32x32x16_bf16 v[0:15], v[228:231], v[80:83], v[0:15]
	v_add_f32_e32 v189, v189, v90
	v_add_f32_e32 v189, v189, v91
	v_add_f32_e32 v189, v189, v92
	v_add_f32_e32 v189, v189, v93
	v_add_f32_e32 v189, v189, v94
	v_add_f32_e32 v189, v189, v95
	v_cvt_pk_bf16_f32 v84, v88, v89
	v_cvt_pk_bf16_f32 v85, v90, v91
	v_cvt_pk_bf16_f32 v86, v92, v93
	v_cvt_pk_bf16_f32 v87, v94, v95
	s_nop 0
	s_waitcnt lgkmcnt(0)
	v_mfma_f32_32x32x16_bf16 v[48:63], v[232:235], v[84:87], v[48:63]
	v_mfma_f32_32x32x16_bf16 v[32:47], v[236:239], v[84:87], v[32:47]
	v_mfma_f32_32x32x16_bf16 v[16:31], v[240:243], v[84:87], v[16:31]
	v_mfma_f32_32x32x16_bf16 v[0:15], v[244:247], v[84:87], v[0:15]
	s_waitcnt vmcnt(0)
	s_barrier
	ds_read_b128 v[64:67], v173 offset:0
	ds_read_b128 v[68:71], v173 offset:4096
	s_add_u32 m0, s44, 0x6000
	ds_read_b128 v[72:75], v171 offset:0
	global_load_lds_dwordx4 v200, s[40:41]
	s_add_u32 m0, s44, 0x6400
	ds_read_b128 v[76:79], v171 offset:4096
	global_load_lds_dwordx4 v190, s[40:41]
	s_add_u32 m0, s45, 0x6000
	ds_read_b128 v[216:219], v169 offset:0
	global_load_lds_dwordx4 v192, s[42:43]
	s_add_u32 m0, s45, 0x6400
	ds_read_b128 v[220:223], v169 offset:4096
	global_load_lds_dwordx4 v194, s[42:43]
	s_add_u32 m0, s45, 0x6800
	ds_read_b128 v[224:227], v167 offset:0
	global_load_lds_dwordx4 v196, s[42:43]
	s_add_u32 m0, s45, 0x6c00
	ds_read_b128 v[228:231], v167 offset:4096
	global_load_lds_dwordx4 v198, s[42:43]
	ds_read_b128 v[232:235], v173 offset:8192
	ds_read_b128 v[236:239], v173 offset:12288
	ds_read_b128 v[240:243], v173 offset:16384
	ds_read_b128 v[244:247], v173 offset:20480
	s_add_u32 s40, s40, 0x18000
	s_addc_u32 s41, s41, 0
	s_add_u32 s42, s42, 0x80
	s_addc_u32 s43, s43, 0
	s_waitcnt lgkmcnt(11)
	v_mfma_f32_32x32x16_bf16 v[112:127], v[64:67], v[140:143], v[96:111]
	ds_read_b128 v[64:67], v171 offset:8192
	s_waitcnt lgkmcnt(11)
	v_mfma_f32_32x32x16_bf16 v[80:95], v[68:71], v[140:143], v[96:111]
	ds_read_b128 v[68:71], v171 offset:12288
	s_waitcnt lgkmcnt(11)
	v_mfma_f32_32x32x16_bf16 v[112:127], v[72:75], v[136:139], v[112:127]
	ds_read_b128 v[72:75], v171 offset:16384
	s_waitcnt lgkmcnt(11)
	v_mfma_f32_32x32x16_bf16 v[80:95], v[76:79], v[136:139], v[80:95]
	ds_read_b128 v[76:79], v171 offset:20480
	s_waitcnt lgkmcnt(11)
	v_mfma_f32_32x32x16_bf16 v[112:127], v[216:219], v[132:135], v[112:127]
	ds_read_b128 v[216:219], v169 offset:8192
	s_waitcnt lgkmcnt(11)
	v_mfma_f32_32x32x16_bf16 v[80:95], v[220:223], v[132:135], v[80:95]
	ds_read_b128 v[220:223], v169 offset:12288
	s_waitcnt lgkmcnt(11)
	v_mfma_f32_32x32x16_bf16 v[112:127], v[224:227], v[128:131], v[112:127]
	ds_read_b128 v[224:227], v169 offset:16384
	s_waitcnt lgkmcnt(11)
	v_mfma_f32_32x32x16_bf16 v[80:95], v[228:231], v[128:131], v[80:95]
	ds_read_b128 v[228:231], v169 offset:20480
	s_nop 7
	s_nop 3
	v_max3_f32 v175, v112, v113, v114
	v_max3_f32 v177, v115, v116, v117
	v_max3_f32 v179, v118, v119, v120
	v_max3_f32 v181, v121, v122, v123
	v_max3_f32 v248, v124, v125, v126
	v_max3_f32 v249, v127, v80, v81
	v_max3_f32 v250, v82, v83, v84
	v_max3_f32 v251, v85, v86, v87
	v_max3_f32 v253, v88, v89, v90
	v_max3_f32 v254, v91, v92, v93
	v_max3_f32 v175, v175, v177, v179
	v_max3_f32 v181, v181, v248, v249
	v_max3_f32 v250, v250, v251, v253
	v_max3_f32 v254, v254, v94, v95
	v_max3_f32 v175, v175, v181, v250
	v_max_f32_e32 v175, v175, v254
	v_cmp_lt_f32_e32 vcc, 0x41000000, v175
	s_cbranch_vccnz .Latt_resc_b
.Latt_cont_b:
	v_exp_f32_e32 v112, v112
	v_exp_f32_e32 v113, v113
	v_exp_f32_e32 v114, v114
	v_exp_f32_e32 v115, v115
	v_exp_f32_e32 v116, v116
	v_exp_f32_e32 v117, v117
	v_exp_f32_e32 v118, v118
	v_exp_f32_e32 v119, v119
	v_add_f32_e32 v189, v189, v112
	v_add_f32_e32 v189, v189, v113
	v_add_f32_e32 v189, v189, v114
	v_add_f32_e32 v189, v189, v115
	v_add_f32_e32 v189, v189, v116
	v_add_f32_e32 v189, v189, v117
	v_add_f32_e32 v189, v189, v118
	v_add_f32_e32 v189, v189, v119
	v_cvt_pk_bf16_f32 v112, v112, v113
	v_cvt_pk_bf16_f32 v113, v114, v115
	v_cvt_pk_bf16_f32 v114, v116, v117
	v_cvt_pk_bf16_f32 v115, v118, v119
	v_exp_f32_e32 v120, v120
	v_exp_f32_e32 v121, v121
	s_waitcnt lgkmcnt(8)
	v_mfma_f32_32x32x16_bf16 v[48:63], v[232:235], v[112:115], v[48:63]
	v_exp_f32_e32 v122, v122
	v_exp_f32_e32 v123, v123
	v_exp_f32_e32 v124, v124
	v_mfma_f32_32x32x16_bf16 v[32:47], v[236:239], v[112:115], v[32:47]
	v_exp_f32_e32 v125, v125
	v_exp_f32_e32 v126, v126
	v_exp_f32_e32 v127, v127
	v_mfma_f32_32x32x16_bf16 v[16:31], v[240:243], v[112:115], v[16:31]
	v_add_f32_e32 v189, v189, v120
	v_add_f32_e32 v189, v189, v121
	v_add_f32_e32 v189, v189, v122
	v_add_f32_e32 v189, v189, v123
	v_add_f32_e32 v189, v189, v124
	v_add_f32_e32 v189, v189, v125
	v_mfma_f32_32x32x16_bf16 v[0:15], v[244:247], v[112:115], v[0:15]
	ds_read_b128 v[232:235], v167 offset:8192
	ds_read_b128 v[236:239], v167 offset:12288
	ds_read_b128 v[240:243], v167 offset:16384
	ds_read_b128 v[244:247], v167 offset:20480
	v_add_f32_e32 v189, v189, v126
	v_add_f32_e32 v189, v189, v127
	v_cvt_pk_bf16_f32 v116, v120, v121
	v_cvt_pk_bf16_f32 v117, v122, v123
	v_cvt_pk_bf16_f32 v118, v124, v125
	v_cvt_pk_bf16_f32 v119, v126, v127
	s_nop 0
	s_waitcnt lgkmcnt(8)
	v_mfma_f32_32x32x16_bf16 v[48:63], v[64:67], v[116:119], v[48:63]
	v_exp_f32_e32 v80, v80
	v_exp_f32_e32 v81, v81
	v_exp_f32_e32 v82, v82
	v_mfma_f32_32x32x16_bf16 v[32:47], v[68:71], v[116:119], v[32:47]
	v_exp_f32_e32 v83, v83
	v_exp_f32_e32 v84, v84
	v_exp_f32_e32 v85, v85
	v_mfma_f32_32x32x16_bf16 v[16:31], v[72:75], v[116:119], v[16:31]
	v_exp_f32_e32 v86, v86
	v_exp_f32_e32 v87, v87
	v_add_f32_e32 v189, v189, v80
	v_add_f32_e32 v189, v189, v81
	v_mfma_f32_32x32x16_bf16 v[0:15], v[76:79], v[116:119], v[0:15]
	v_add_f32_e32 v189, v189, v82
	v_add_f32_e32 v189, v189, v83
	v_add_f32_e32 v189, v189, v84
	v_add_f32_e32 v189, v189, v85
	v_add_f32_e32 v189, v189, v86
	v_add_f32_e32 v189, v189, v87
	v_cvt_pk_bf16_f32 v80, v80, v81
	v_cvt_pk_bf16_f32 v81, v82, v83
	v_cvt_pk_bf16_f32 v82, v84, v85
	v_cvt_pk_bf16_f32 v83, v86, v87
	s_nop 0
	s_waitcnt lgkmcnt(4)
	v_mfma_f32_32x32x16_bf16 v[48:63], v[216:219], v[80:83], v[48:63]
	v_exp_f32_e32 v88, v88
	v_exp_f32_e32 v89, v89
	v_exp_f32_e32 v90, v90
	v_mfma_f32_32x32x16_bf16 v[32:47], v[220:223], v[80:83], v[32:47]
	v_exp_f32_e32 v91, v91
	v_exp_f32_e32 v92, v92
	v_exp_f32_e32 v93, v93
	v_mfma_f32_32x32x16_bf16 v[16:31], v[224:227], v[80:83], v[16:31]
	v_exp_f32_e32 v94, v94
	v_exp_f32_e32 v95, v95
	v_add_f32_e32 v189, v189, v88
	v_add_f32_e32 v189, v189, v89
	v_mfma_f32_32x32x16_bf16 v[0:15], v[228:231], v[80:83], v[0:15]
	v_add_f32_e32 v189, v189, v90
	v_add_f32_e32 v189, v189, v91
	v_add_f32_e32 v189, v189, v92
	v_add_f32_e32 v189, v189, v93
	v_add_f32_e32 v189, v189, v94
	v_add_f32_e32 v189, v189, v95
	v_cvt_pk_bf16_f32 v84, v88, v89
	v_cvt_pk_bf16_f32 v85, v90, v91
	v_cvt_pk_bf16_f32 v86, v92, v93
	v_cvt_pk_bf16_f32 v87, v94, v95
	s_nop 0
	s_waitcnt lgkmcnt(0)
	v_mfma_f32_32x32x16_bf16 v[48:63], v[232:235], v[84:87], v[48:63]
	v_mfma_f32_32x32x16_bf16 v[32:47], v[236:239], v[84:87], v[32:47]
	v_mfma_f32_32x32x16_bf16 v[16:31], v[240:243], v[84:87], v[16:31]
	v_mfma_f32_32x32x16_bf16 v[0:15], v[244:247], v[84:87], v[0:15]
	s_sub_u32 s46, s46, 1
	s_cmp_lg_u32 s46, 0
	s_cbranch_scc1 .Latt_loop
	v_mov_b64_e32 v[64:65], v[96:97]
	v_mov_b64_e32 v[66:67], v[98:99]
	v_mov_b64_e32 v[68:69], v[100:101]
	v_mov_b64_e32 v[70:71], v[102:103]
	v_mov_b64_e32 v[72:73], v[104:105]
	v_mov_b64_e32 v[74:75], v[106:107]
	v_mov_b64_e32 v[76:77], v[108:109]
	v_mov_b64_e32 v[78:79], v[110:111]
	v_mov_b32_e32 v248, v189
	s_nop 1
	v_permlane32_swap_b32_e32 v189, v248
	v_add_f32_e32 v189, v189, v248
	s_branch .LBB0_1482
